# hyena unit: the x0 rows needed after the main loop are loaded into unused registers before the main loop (latency hidden behind the MFMA loop), on top of v50
# baseline (speedup 1.0000x reference)
.LBB0_496:
	v_ashrrev_i32_e32 v83, 31, v2
	v_lshrrev_b32_e32 v83, 22, v83
	v_add_u32_e32 v83, v2, v83
	v_ashrrev_i32_e32 v88, 10, v83
	v_ashrrev_i32_e32 v89, 31, v88
	v_mul_i32_i24_e32 v83, 0x400, v88
	v_lshlrev_b64 v[84:85], 8, v[88:89]
	v_sub_u32_e32 v92, v2, v83
	v_lshlrev_b32_e32 v83, 3, v83
	v_lshl_add_u64 v[84:85], v[84:85], 0, s[2:3]
	v_mov_b64_e32 v[86:87], s[18:19]
	v_sub_u32_e32 v90, v0, v83
	v_mad_u64_u32 v[86:87], s[0:1], v84, s95, v[86:87]
	v_mad_i32_i24 v87, v85, s95, v87
	v_ashrrev_i32_e32 v91, 31, v90
	v_lshl_add_u64 v[84:85], v[90:91], 1, v[86:87]
	global_load_dwordx4 v[84:87], v[84:85], off offset:512
	v_mov_b32_e32 v83, s8
	v_mad_i32_i24 v83, v88, s9, v83
	v_lshrrev_b32_e32 v88, 3, v92
	v_and_b32_e32 v89, 56, v90
	v_mul_lo_u32 v88, v88, s57
	v_lshlrev_b32_e32 v89, 1, v89
	v_add3_u32 v83, v83, v88, v89
	v_add_u32_e32 v0, 0x1000, v0
	v_add_u32_e32 v2, 0x200, v2
	v_ashrrev_i32_e32 v95, 31, v2
	v_lshrrev_b32_e32 v95, 22, v95
	v_add_u32_e32 v95, v2, v95
	v_ashrrev_i32_e32 v100, 10, v95
	v_ashrrev_i32_e32 v101, 31, v100
	v_mul_i32_i24_e32 v95, 0x400, v100
	v_lshlrev_b64 v[96:97], 8, v[100:101]
	v_sub_u32_e32 v104, v2, v95
	v_lshlrev_b32_e32 v95, 3, v95
	v_lshl_add_u64 v[96:97], v[96:97], 0, s[2:3]
	v_mov_b64_e32 v[98:99], s[18:19]
	v_sub_u32_e32 v102, v0, v95
	v_mad_u64_u32 v[98:99], s[0:1], v96, s95, v[98:99]
	v_mad_i32_i24 v99, v97, s95, v99
	v_ashrrev_i32_e32 v103, 31, v102
	v_lshl_add_u64 v[96:97], v[102:103], 1, v[98:99]
	global_load_dwordx4 v[96:99], v[96:97], off offset:512
	v_mov_b32_e32 v95, s8
	v_mad_i32_i24 v95, v100, s9, v95
	v_lshrrev_b32_e32 v100, 3, v104
	v_and_b32_e32 v101, 56, v102
	v_mul_lo_u32 v100, v100, s57
	v_lshlrev_b32_e32 v101, 1, v101
	v_add3_u32 v95, v95, v100, v101
	v_add_u32_e32 v0, 0x1000, v0
	v_add_u32_e32 v2, 0x200, v2
	v_ashrrev_i32_e32 v107, 31, v2
	v_lshrrev_b32_e32 v107, 22, v107
	v_add_u32_e32 v107, v2, v107
	v_ashrrev_i32_e32 v112, 10, v107
	v_ashrrev_i32_e32 v113, 31, v112
	v_mul_i32_i24_e32 v107, 0x400, v112
	v_lshlrev_b64 v[108:109], 8, v[112:113]
	v_sub_u32_e32 v116, v2, v107
	v_lshlrev_b32_e32 v107, 3, v107
	v_lshl_add_u64 v[108:109], v[108:109], 0, s[2:3]
	v_mov_b64_e32 v[110:111], s[18:19]
	v_sub_u32_e32 v114, v0, v107
	v_mad_u64_u32 v[110:111], s[0:1], v108, s95, v[110:111]
	v_mad_i32_i24 v111, v109, s95, v111
	v_ashrrev_i32_e32 v115, 31, v114
	v_lshl_add_u64 v[108:109], v[114:115], 1, v[110:111]
	global_load_dwordx4 v[108:111], v[108:109], off offset:512
	v_mov_b32_e32 v107, s8
	v_mad_i32_i24 v107, v112, s9, v107
	v_lshrrev_b32_e32 v112, 3, v116
	v_and_b32_e32 v113, 56, v114
	v_mul_lo_u32 v112, v112, s57
	v_lshlrev_b32_e32 v113, 1, v113
	v_add3_u32 v107, v107, v112, v113
	v_add_u32_e32 v0, 0x1000, v0
	v_add_u32_e32 v2, 0x200, v2
	v_ashrrev_i32_e32 v119, 31, v2
	v_lshrrev_b32_e32 v119, 22, v119
	v_add_u32_e32 v119, v2, v119
	v_ashrrev_i32_e32 v124, 10, v119
	v_ashrrev_i32_e32 v125, 31, v124
	v_mul_i32_i24_e32 v119, 0x400, v124
	v_lshlrev_b64 v[120:121], 8, v[124:125]
	v_sub_u32_e32 v128, v2, v119
	v_lshlrev_b32_e32 v119, 3, v119
	v_lshl_add_u64 v[120:121], v[120:121], 0, s[2:3]
	v_mov_b64_e32 v[122:123], s[18:19]
	v_sub_u32_e32 v126, v0, v119
	v_mad_u64_u32 v[122:123], s[0:1], v120, s95, v[122:123]
	v_mad_i32_i24 v123, v121, s95, v123
	v_ashrrev_i32_e32 v127, 31, v126
	v_lshl_add_u64 v[120:121], v[126:127], 1, v[122:123]
	global_load_dwordx4 v[120:123], v[120:121], off offset:512
	v_mov_b32_e32 v119, s8
	v_mad_i32_i24 v119, v124, s9, v119
	v_lshrrev_b32_e32 v124, 3, v128
	v_and_b32_e32 v125, 56, v126
	v_mul_lo_u32 v124, v124, s57
	v_lshlrev_b32_e32 v125, 1, v125
	v_add3_u32 v119, v119, v124, v125
	v_add_u32_e32 v0, 0x1000, v0
	v_add_u32_e32 v2, 0x200, v2
	s_waitcnt vmcnt(3)
	ds_write_b128 v83, v[84:87] offset:2304
	s_waitcnt vmcnt(2)
	ds_write_b128 v95, v[96:99] offset:2304
	s_waitcnt vmcnt(1)
	ds_write_b128 v107, v[108:111] offset:2304
	s_waitcnt vmcnt(0)
	ds_write_b128 v119, v[120:123] offset:2304
	v_mov_b32_e32 v178, v77
	v_mov_b32_e32 v179, v76
	v_lshl_add_u32 v180, v77, 4, 0
	v_readlane_b32 s36, v251, 35
	v_readlane_b32 s37, v251, 36
	s_nop 3
	v_ashrrev_i32_e32 v132, 31, v178
	v_lshrrev_b32_e32 v132, 22, v132
	v_add_u32_e32 v132, v178, v132
	v_ashrrev_i32_e32 v134, 10, v132
	v_ashrrev_i32_e32 v135, 31, v134
	v_mul_i32_i24_e32 v138, 0x400, v134
	v_lshlrev_b64 v[132:133], 8, v[134:135]
	v_mov_b64_e32 v[130:131], s[36:37]
	v_lshlrev_b32_e32 v136, 3, v138
	v_lshl_add_u64 v[132:133], v[132:133], 0, s[2:3]
	v_sub_u32_e32 v136, v179, v136
	v_mad_u64_u32 v[130:131], s[38:39], v132, s95, v[130:131]
	v_ashrrev_i32_e32 v137, 31, v136
	v_mad_i32_i24 v131, v133, s95, v131
	v_lshl_add_u64 v[130:131], v[136:137], 1, v[130:131]
	global_load_dwordx4 v[130:133], v[130:131], off offset:512
	v_add_u32_e32 v178, 0x200, v178
	v_lshlrev_b32_e32 v134, 14, v134
	v_lshlrev_b32_e32 v135, 4, v138
	v_sub_u32_e32 v134, v134, v135
	v_add_u32_e32 v179, 0x1000, v179
	v_add_u32_e32 v134, v180, v134
	v_add_u32_e32 v180, 0x2000, v180
	v_ashrrev_i32_e32 v144, 31, v178
	v_lshrrev_b32_e32 v144, 22, v144
	v_add_u32_e32 v144, v178, v144
	v_ashrrev_i32_e32 v146, 10, v144
	v_ashrrev_i32_e32 v147, 31, v146
	v_mul_i32_i24_e32 v150, 0x400, v146
	v_lshlrev_b64 v[144:145], 8, v[146:147]
	v_mov_b64_e32 v[142:143], s[36:37]
	v_lshlrev_b32_e32 v148, 3, v150
	v_lshl_add_u64 v[144:145], v[144:145], 0, s[2:3]
	v_sub_u32_e32 v148, v179, v148
	v_mad_u64_u32 v[142:143], s[38:39], v144, s95, v[142:143]
	v_ashrrev_i32_e32 v149, 31, v148
	v_mad_i32_i24 v143, v145, s95, v143
	v_lshl_add_u64 v[142:143], v[148:149], 1, v[142:143]
	global_load_dwordx4 v[142:145], v[142:143], off offset:512
	v_add_u32_e32 v178, 0x200, v178
	v_lshlrev_b32_e32 v146, 14, v146
	v_lshlrev_b32_e32 v147, 4, v150
	v_sub_u32_e32 v146, v146, v147
	v_add_u32_e32 v179, 0x1000, v179
	v_add_u32_e32 v146, v180, v146
	v_add_u32_e32 v180, 0x2000, v180
	v_ashrrev_i32_e32 v156, 31, v178
	v_lshrrev_b32_e32 v156, 22, v156
	v_add_u32_e32 v156, v178, v156
	v_ashrrev_i32_e32 v158, 10, v156
	v_ashrrev_i32_e32 v159, 31, v158
	v_mul_i32_i24_e32 v162, 0x400, v158
	v_lshlrev_b64 v[156:157], 8, v[158:159]
	v_mov_b64_e32 v[154:155], s[36:37]
	v_lshlrev_b32_e32 v160, 3, v162
	v_lshl_add_u64 v[156:157], v[156:157], 0, s[2:3]
	v_sub_u32_e32 v160, v179, v160
	v_mad_u64_u32 v[154:155], s[38:39], v156, s95, v[154:155]
	v_ashrrev_i32_e32 v161, 31, v160
	v_mad_i32_i24 v155, v157, s95, v155
	v_lshl_add_u64 v[154:155], v[160:161], 1, v[154:155]
	global_load_dwordx4 v[154:157], v[154:155], off offset:512
	v_add_u32_e32 v178, 0x200, v178
	v_lshlrev_b32_e32 v158, 14, v158
	v_lshlrev_b32_e32 v159, 4, v162
	v_sub_u32_e32 v158, v158, v159
	v_add_u32_e32 v179, 0x1000, v179
	v_add_u32_e32 v158, v180, v158
	v_add_u32_e32 v180, 0x2000, v180
	v_ashrrev_i32_e32 v168, 31, v178
	v_lshrrev_b32_e32 v168, 22, v168
	v_add_u32_e32 v168, v178, v168
	v_ashrrev_i32_e32 v170, 10, v168
	v_ashrrev_i32_e32 v171, 31, v170
	v_mul_i32_i24_e32 v174, 0x400, v170
	v_lshlrev_b64 v[168:169], 8, v[170:171]
	v_mov_b64_e32 v[166:167], s[36:37]
	v_lshlrev_b32_e32 v172, 3, v174
	v_lshl_add_u64 v[168:169], v[168:169], 0, s[2:3]
	v_sub_u32_e32 v172, v179, v172
	v_mad_u64_u32 v[166:167], s[38:39], v168, s95, v[166:167]
	v_ashrrev_i32_e32 v173, 31, v172
	v_mad_i32_i24 v167, v169, s95, v167
	v_lshl_add_u64 v[166:167], v[172:173], 1, v[166:167]
	global_load_dwordx4 v[166:169], v[166:167], off offset:512
	v_add_u32_e32 v178, 0x200, v178
	v_lshlrev_b32_e32 v170, 14, v170
	v_lshlrev_b32_e32 v171, 4, v174
	v_sub_u32_e32 v170, v170, v171
	v_add_u32_e32 v179, 0x1000, v179
	v_add_u32_e32 v170, v180, v170
	v_add_u32_e32 v180, 0x2000, v180

.LBB0_506:
	s_waitcnt vmcnt(0)
	ds_write_b128 v134, v[130:133]
	ds_write_b128 v146, v[142:145]
	ds_write_b128 v158, v[154:157]
	ds_write_b128 v170, v[166:169]
	s_branch .LBB0_472
